# e26: no-straddle nops in B-loop + HGRN chunk-state/output loops, 8-byte parity of later code preserved
# baseline (speedup 1.0000x reference)
; __device__ __forceinline__ float h2f(unsigned short u) { return (float)__builtin_bit_cast(_Float16, u); }
; #define LDS_WAIT() asm volatile("s_waitcnt lgkmcnt(0)" ::: "memory")
; __device__ __forceinline__ void hgrn_prep64(char* lds, int s, int w, int kc, int tq, float& gsum, bf16x8 (&vf)[2]) {
;     const int buf = s & 1; const char* raw = lds + buf * 49152; char* KDT = lds + 98304 + buf * 16384; float* DL = (float*)(lds + 131072 + buf * 512);
;     const int ch = 16 * w + kc;
;     float lf[2][8];
; #pragma unroll
;     for (int hf = 0; hf < 2; ++hf)
; #pragma unroll
;         for (int jj = 0; jj < 8; ++jj) { const int t = 32 * hf + 8 * tq + jj; lf[hf][jj] = h2f(*(const unsigned short*)(raw + (t * 128 + ch) * 2));
;             vf[hf][jj] = (short)*(const unsigned short*)(raw + 32768 + (t * 128 + ch) * 2); }
;     float c[2][8];
; #pragma unroll
;     for (int hf = 0; hf < 2; ++hf) { c[hf][0] = lf[hf][0];
; #pragma unroll
;         for (int jj = 1; jj < 8; ++jj) c[hf][jj] = c[hf][jj - 1] + lf[hf][jj]; }
;     const float R0 = c[0][7], R1 = c[1][7];
;     float P0, T0, p1_, t1_; row_prefix4(R0, tq, P0, T0); row_prefix4(R1, tq, p1_, t1_);
; __device__ __forceinline__ void hgrn_state_item64(const float* __restrict__ LOGF, const bf16* __restrict__ V, int row0, int nsteps, int h, bf16* __restrict__ Sout, float* __restrict__ Dout, char* lds) {
;     ...
;     bf16x8 vf_cur[2], vf_nxt[2];
;     HG_DMA(0, 0); if (1 < nsteps) HG_DMA(1, 1);
;     asm volatile("s_waitcnt vmcnt(0)" ::: "memory"); __builtin_amdgcn_s_barrier(); asm volatile("" ::: "memory");
;     hgrn_prep64(lds, 0, w, kc, tq, gsum, vf_cur);
;     LDS_WAIT(); __builtin_amdgcn_s_barrier(); asm volatile("" ::: "memory");
.LBB0_2170:
	v_mov_b32_e32 v13, v0
	s_ashr_i32 s47, s46, 4
	s_lshl_b32 s4, s47, 10
	v_readfirstlane_b32 s5, v13
	s_ashr_i32 s6, s5, 6
	v_bfe_u32 v53, v13, 4, 2
	s_lshl_b32 s5, s6, 3
	v_or_b32_e32 v2, s4, v53
	v_add_u32_e32 v4, s5, v2
	v_ashrrev_i32_e32 v5, 31, v4
	s_and_b32 s19, s46, 15
	v_lshlrev_b64 v[4:5], 12, v[4:5]
	v_and_b32_e32 v56, 15, v13
	v_lshl_add_u64 v[6:7], s[12:13], 0, v[4:5]
	s_lshl_b32 s10, s19, 8
	v_lshl_add_u64 v[4:5], s[2:3], 0, v[4:5]
	s_lshl_b32 s7, s6, 11
	v_lshl_add_u64 v[6:7], v[6:7], 0, s[10:11]
	v_lshlrev_b32_e32 v2, 4, v56
	v_lshl_add_u64 v[4:5], v[4:5], 0, s[10:11]
	s_add_i32 s10, s7, 0
	v_lshl_add_u64 v[6:7], v[6:7], 0, v[2:3]
	s_mov_b32 m0, s10
	s_mov_b64 s[8:9], 0x4000
	global_load_lds_dwordx4 v[6:7], off
	v_lshl_add_u64 v[8:9], v[6:7], 0, s[8:9]
	s_add_i32 m0, s10, 0x400
	v_lshl_add_u64 v[4:5], v[4:5], 0, v[2:3]
	global_load_lds_dwordx4 v[8:9], off
	s_add_i32 m0, s10, 0x8000
	v_lshl_add_u64 v[8:9], v[4:5], 0, s[8:9]
	global_load_lds_dwordx4 v[4:5], off
	s_add_i32 m0, s10, 0x8400
	s_mov_b64 s[8:9], 0x44000
	global_load_lds_dwordx4 v[8:9], off
	s_add_i32 m0, s10, 0xc000
	v_lshl_add_u64 v[8:9], v[6:7], 0, s[60:61]
	global_load_lds_dwordx4 v[8:9], off
	v_lshl_add_u64 v[6:7], v[6:7], 0, s[8:9]
	s_add_i32 m0, s10, 0xc400
	s_lshl_b32 s18, s6, 4
	global_load_lds_dwordx4 v[6:7], off
	s_add_i32 m0, s10, 0x14000
	v_lshl_add_u64 v[6:7], v[4:5], 0, s[60:61]
	s_nop 0
	global_load_lds_dwordx4 v[6:7], off
	v_lshl_add_u64 v[4:5], v[4:5], 0, s[8:9]
	s_add_i32 m0, s10, 0x14400
	v_or_b32_e32 v52, s18, v56
	global_load_lds_dwordx4 v[4:5], off
	v_lshlrev_b32_e32 v4, 11, v53
	v_lshlrev_b32_e32 v5, 1, v52
	s_waitcnt vmcnt(0)
	s_barrier
	v_add3_u32 v57, v5, v4, 0
	s_nop 0
	ds_read_u16 v4, v57
	ds_read_u16 v5, v57 offset:256
	ds_read_u16 v6, v57 offset:512
	ds_read_u16 v7, v57 offset:768
	ds_read_u16 v8, v57 offset:1024
	ds_read_u16 v9, v57 offset:1280
	ds_read_u16 v10, v57 offset:1536
	ds_read_u16 v11, v57 offset:1792
	s_waitcnt lgkmcnt(0)
	v_cvt_f32_f16_e32 v46, v4
	v_cvt_f32_f16_e32 v48, v5
	v_cvt_f32_f16_e32 v45, v6
	v_cvt_f32_f16_e32 v40, v7
	v_cvt_f32_f16_e32 v30, v11
	ds_read_u16 v14, v57 offset:32768
	ds_read_u16 v15, v57 offset:33024
	ds_read_u16 v16, v57 offset:33280
	ds_read_u16 v17, v57 offset:33536
	ds_read_u16 v18, v57 offset:33792
	ds_read_u16 v19, v57 offset:34048
	ds_read_u16 v20, v57 offset:34304
	ds_read_u16 v21, v57 offset:34560
	ds_read_u16 v11, v57 offset:8192
	ds_read_u16 v12, v57 offset:8448
	ds_read_u16 v32, v57 offset:8704
	ds_read_u16 v34, v57 offset:8960
	ds_read_u16 v35, v57 offset:9216
	ds_read_u16 v36, v57 offset:9472
	ds_read_u16 v44, v57 offset:9728
	ds_read_u16 v47, v57 offset:9984
	ds_read_u16 v22, v57 offset:40960
	ds_read_u16 v23, v57 offset:41216
	ds_read_u16 v24, v57 offset:41472
	ds_read_u16 v25, v57 offset:41728
	ds_read_u16 v26, v57 offset:41984
	ds_read_u16 v27, v57 offset:42240
	ds_read_u16 v28, v57 offset:42496
	ds_read_u16 v29, v57 offset:42752
	v_cvt_f32_f16_e32 v38, v8
	v_cvt_f32_f16_e32 v6, v9
	v_add_f32_e32 v49, v46, v48
	v_cvt_f32_f16_e32 v4, v10
	v_add_f32_e32 v42, v49, v45
	v_add_f32_e32 v41, v42, v40
	v_add_f32_e32 v39, v41, v38
	v_add_f32_e32 v33, v39, v6
	v_add_f32_e32 v5, v33, v4
	v_add_f32_e32 v31, v5, v30
	v_mov_b32_e32 v9, v31
	v_mov_b32_e32 v7, v31
	s_nop 1
	v_permlane16_swap_b32_e32 v9, v7
	v_add_f32_e32 v8, v9, v7
	v_mov_b32_e32 v10, v8
	s_nop 1
	v_permlane32_swap_b32_e32 v8, v10
	v_cmp_lt_i32_e32 vcc, 0, v53
	v_mov_b32_e32 v7, 0
	s_and_saveexec_b64 s[20:21], vcc
	s_cbranch_execz .LBB0_2176
	v_cmp_ne_u32_e32 vcc, 1, v53
	s_and_saveexec_b64 s[6:7], vcc
	s_xor_b64 s[36:37], exec, s[6:7]
	v_add_f32_e32 v7, v9, v8
	v_cmp_eq_u32_e32 vcc, 2, v53
	s_nop 1
	v_cndmask_b32_e32 v7, v7, v8, vcc
	s_andn2_saveexec_b64 s[36:37], s[36:37]
	v_mov_b32_e32 v7, v9
	s_or_b64 exec, exec, s[36:37]

; __device__ __forceinline__ unsigned cvt_pk_bf16(float lo, float hi) { unsigned r; asm volatile("v_cvt_pk_bf16_f32 %0, %1, %2" : "=v"(r) : "v"(lo), "v"(hi)); return r; }
; #define LDS_WAIT() asm volatile("s_waitcnt lgkmcnt(0)" ::: "memory")
; __device__ __forceinline__ void hgrn_prep64(char* lds, int s, int w, int kc, int tq, float& gsum, bf16x8 (&vf)[2]) {
;     ...
;     const float P1 = T0 + p1_, glast = T0 + t1_;
; #pragma unroll
;     for (int hf = 0; hf < 2; ++hf) { const float P = hf ? P1 : P0; float kd[8];
; #pragma unroll
;         for (int jj = 0; jj < 8; ++jj) kd[jj] = (1.f - __builtin_amdgcn_exp2f(lf[hf][jj])) * __builtin_amdgcn_exp2f(glast - (P + c[hf][jj]));
;         u32x4 kw; kw.x = cvt_pk_bf16(kd[0], kd[1]); kw.y = cvt_pk_bf16(kd[2], kd[3]); kw.z = cvt_pk_bf16(kd[4], kd[5]); kw.w = cvt_pk_bf16(kd[6], kd[7]);
;         *(u32x4*)(KDT + ch * 128 + (((4 * hf + tq) ^ (ch & 7)) << 4)) = kw; }
;     DL[ch] = __builtin_amdgcn_exp2f(glast);
;     gsum += glast;
; }
; __device__ __forceinline__ void hgrn_state_item64(const float* __restrict__ LOGF, const bf16* __restrict__ V, int row0, int nsteps, int h, bf16* __restrict__ Sout, float* __restrict__ Dout, char* lds) {
;     ...
;     bf16x8 vf_cur[2], vf_nxt[2];
;     HG_DMA(0, 0); if (1 < nsteps) HG_DMA(1, 1);
;     asm volatile("s_waitcnt vmcnt(0)" ::: "memory"); __builtin_amdgcn_s_barrier(); asm volatile("" ::: "memory");
;     hgrn_prep64(lds, 0, w, kc, tq, gsum, vf_cur);
;     LDS_WAIT(); __builtin_amdgcn_s_barrier(); asm volatile("" ::: "memory");
; #pragma unroll 1
;     for (int s = 0; s < nsteps; ++s) {
.LBB0_2182:
	s_or_b64 exec, exec, s[20:21]
	s_nop 0
	v_pk_add_f32 v[8:9], v[8:9], v[10:11]
	v_exp_f32_e32 v60, v6
	v_exp_f32_e32 v64, v4
	v_mov_b32_e32 v4, v8
	v_mov_b32_e32 v6, v9
	v_add_f32_e32 v10, v8, v59
	v_exp_f32_e32 v11, v46
	v_add_f32_e32 v46, v7, v46
	v_pk_add_f32 v[8:9], v[4:5], v[6:7]
	v_add_f32_e32 v6, v33, v7
	v_sub_f32_e32 v4, v8, v46
	v_exp_f32_e32 v4, v4
	v_add_f32_e32 v49, v49, v7
	v_add_f32_e32 v42, v42, v7
	v_add_f32_e32 v41, v41, v7
	v_add_f32_e32 v39, v39, v7
	v_sub_f32_e32 v6, v8, v6
	v_add_f32_e32 v7, v31, v7
	v_sub_f32_e32 v11, 1.0, v11
	v_exp_f32_e32 v6, v6
	v_sub_f32_e32 v9, v8, v9
	v_exp_f32_e32 v30, v30
	v_sub_f32_e32 v7, v8, v7
	v_exp_f32_e32 v48, v48
	v_exp_f32_e32 v45, v45
	v_exp_f32_e32 v40, v40
	v_exp_f32_e32 v38, v38
	v_mul_f32_e32 v4, v11, v4
	v_sub_f32_e32 v11, v8, v49
	v_sub_f32_e32 v42, v8, v42
	v_sub_f32_e32 v41, v8, v41
	v_sub_f32_e32 v39, v8, v39
	v_exp_f32_e32 v9, v9
	v_exp_f32_e32 v7, v7
	v_exp_f32_e32 v11, v11
	v_exp_f32_e32 v42, v42
	v_exp_f32_e32 v41, v41
	v_exp_f32_e32 v39, v39
	v_sub_f32_e32 v5, 1.0, v60
	v_sub_f32_e32 v33, 1.0, v64
	v_mul_f32_e32 v6, v5, v6
	v_sub_f32_e32 v5, 1.0, v30
	v_sub_f32_e32 v48, 1.0, v48
	v_sub_f32_e32 v45, 1.0, v45
	v_sub_f32_e32 v40, 1.0, v40
	v_sub_f32_e32 v38, 1.0, v38
	v_mul_f32_e32 v9, v33, v9
	v_mul_f32_e32 v7, v5, v7
	s_add_i32 s7, 0, 0x18000
	v_mul_f32_e32 v11, v48, v11
	v_mul_f32_e32 v42, v45, v42
	v_mul_f32_e32 v40, v40, v41
	v_mul_f32_e32 v38, v38, v39
	v_cvt_pk_bf16_f32 v4, v4, v11
	v_cvt_pk_bf16_f32 v5, v42, v40
	v_cvt_pk_bf16_f32 v6, v38, v6
	v_cvt_pk_bf16_f32 v7, v9, v7
	v_bitop3_b32 v9, v53, v13, 7 bitop3:0x78
	v_lshl_add_u32 v59, v52, 7, s7
	v_lshlrev_b32_e32 v60, 4, v9
	v_add_u32_e32 v9, v59, v60
	ds_write_b128 v9, v[4:7]
	v_add_f32_e32 v5, v10, v61
	v_exp_f32_e32 v4, v61
	v_sub_f32_e32 v5, v8, v5
	v_add_f32_e32 v7, v62, v10
	v_exp_f32_e32 v5, v5
	v_exp_f32_e32 v6, v58
	v_sub_f32_e32 v7, v8, v7
	v_exp_f32_e32 v7, v7
	v_sub_f32_e32 v4, 1.0, v4
	v_mul_f32_e32 v4, v4, v5
	v_sub_f32_e32 v5, 1.0, v6
	v_mul_f32_e32 v5, v5, v7
	v_add_f32_e32 v7, v55, v10
	v_exp_f32_e32 v6, v51
	v_sub_f32_e32 v7, v8, v7
	v_add_f32_e32 v11, v54, v10
	v_exp_f32_e32 v7, v7
	v_exp_f32_e32 v9, v50
	v_sub_f32_e32 v11, v8, v11
	v_exp_f32_e32 v11, v11
	v_sub_f32_e32 v6, 1.0, v6
	v_mul_f32_e32 v6, v6, v7
	v_sub_f32_e32 v7, 1.0, v9
	v_mul_f32_e32 v7, v7, v11
	v_add_f32_e32 v11, v47, v10
	v_exp_f32_e32 v9, v43
	v_sub_f32_e32 v11, v8, v11
	v_add_f32_e32 v30, v44, v10
	v_and_b32_e32 v63, 7, v13
	v_exp_f32_e32 v11, v11
	v_exp_f32_e32 v13, v37
	v_sub_f32_e32 v30, v8, v30
	v_exp_f32_e32 v30, v30
	v_sub_f32_e32 v9, 1.0, v9
	v_mul_f32_e32 v9, v9, v11
	v_sub_f32_e32 v11, 1.0, v13
	v_mul_f32_e32 v11, v11, v30
	v_add_f32_e32 v30, v36, v10
	v_exp_f32_e32 v13, v34
	v_sub_f32_e32 v30, v8, v30
	v_add_f32_e32 v10, v35, v10
	v_exp_f32_e32 v30, v30
	v_exp_f32_e32 v31, v32
	v_sub_f32_e32 v10, v8, v10
	v_exp_f32_e32 v10, v10
	v_sub_f32_e32 v13, 1.0, v13
	v_mul_f32_e32 v13, v13, v30
	v_sub_f32_e32 v30, 1.0, v31
	v_cvt_pk_bf16_f32 v4, v4, v5
	v_cvt_pk_bf16_f32 v5, v6, v7
	v_cvt_pk_bf16_f32 v6, v9, v11
	v_bitop3_b32 v9, v53, v63, 4 bitop3:0x36
	v_mul_f32_e32 v10, v30, v10
	v_lshlrev_b32_e32 v61, 4, v9
	v_cvt_pk_bf16_f32 v7, v13, v10
	v_add_u32_e32 v9, v59, v61
	v_exp_f32_e32 v10, v8
	s_add_i32 s4, s4, s5
	ds_write_b128 v9, v[4:7]
	v_add_u32_e32 v4, s4, v53
	s_and_b32 s6, s40, 15
	s_add_i32 s8, 0, 0x20000
	v_ashrrev_i32_e32 v5, 31, v4
	s_lshl_b32 s6, s6, 8
	s_nop 0
	v_lshl_add_u32 v62, v52, 2, s8
	v_lshlrev_b64 v[4:5], 12, v[4:5]
	ds_write_b32 v62, v10
	v_or3_b32 v4, v4, s6, v2
	v_add_f32_e32 v58, 0, v8
	s_waitcnt lgkmcnt(0)
	s_barrier
	v_lshl_add_u64 v[54:55], s[0:1], 0, v[4:5]
	v_mov_b32_e32 v4, v3
	v_mov_b32_e32 v5, v3
	v_mov_b32_e32 v6, v3
	v_mov_b32_e32 v7, v3
	v_mov_b32_e32 v8, v3
	v_mov_b32_e32 v9, v3
	v_mov_b32_e32 v2, v3
	v_mov_b64_e32 v[10:11], v[8:9]
	v_lshl_add_u32 v63, v53, 4, s8
	v_lshl_add_u32 v64, v56, 7, s7
	v_cmp_eq_u32_e32 vcc, 2, v53
	v_perm_b32 v44, v15, v14, s35
	v_perm_b32 v45, v17, v16, s35
	v_perm_b32 v46, v19, v18, s35
	v_perm_b32 v47, v21, v20, s35
	v_perm_b32 v48, v23, v22, s35
	v_perm_b32 v49, v25, v24, s35
	v_perm_b32 v50, v27, v26, s35
	v_perm_b32 v51, v29, v28, s35
	s_mov_b32 s4, 0
	s_mov_b64 s[20:21], 0
	v_mov_b64_e32 v[8:9], v[6:7]
	v_mov_b64_e32 v[6:7], v[4:5]
	v_mov_b64_e32 v[4:5], v[2:3]
	v_mov_b32_e32 v13, v12
	v_mov_b32_e32 v14, v12
	v_mov_b32_e32 v15, v12
	v_mov_b32_e32 v40, v12
	v_mov_b32_e32 v41, v12
	v_mov_b32_e32 v42, v12
	v_mov_b32_e32 v43, v12
	v_mov_b32_e32 v36, v12
	v_mov_b32_e32 v37, v12
	v_mov_b32_e32 v38, v12
	v_mov_b32_e32 v39, v12
	v_mov_b32_e32 v32, v12
	v_mov_b32_e32 v33, v12
	v_mov_b32_e32 v34, v12
	v_mov_b32_e32 v35, v12
	v_mov_b32_e32 v28, v12
	v_mov_b32_e32 v29, v12
	v_mov_b32_e32 v30, v12
	v_mov_b32_e32 v31, v12
	v_mov_b32_e32 v24, v12
	v_mov_b32_e32 v25, v12
	v_mov_b32_e32 v26, v12
	v_mov_b32_e32 v27, v12
	v_mov_b32_e32 v20, v12
	v_mov_b32_e32 v21, v12
	v_mov_b32_e32 v22, v12
	v_mov_b32_e32 v23, v12
	v_mov_b32_e32 v16, v12
	v_mov_b32_e32 v17, v12
	v_mov_b32_e32 v18, v12
	v_mov_b32_e32 v19, v12
	s_cmp_gt_u32 s4, 13
	s_cbranch_scc1 .LBB0_2185
	s_branch .LBB0_2184

; __device__ __forceinline__ void hgrn_state_item64(const float* __restrict__ LOGF, const bf16* __restrict__ V, int row0, int nsteps, int h, bf16* __restrict__ Sout, float* __restrict__ Dout, char* lds) {
;     ...
;         if (s + 2 < nsteps) HG_DMA(s + 2, s & 1);
.LBB0_2184:
	s_bitcmp1_b32 s4, 0
	s_cselect_b32 s5, 0xc000, 0
	s_add_i32 s5, s10, s5
	s_nop 0
	v_lshl_add_u64 v[66:67], v[54:55], 0, s[20:21]
	s_mov_b64 s[6:7], 0x28580000
	v_lshl_add_u64 v[68:69], v[66:67], 0, s[6:7]
	s_mov_b32 m0, s5
	s_mov_b64 s[6:7], 0x28584000
	global_load_lds_dwordx4 v[68:69], off
	v_lshl_add_u64 v[68:69], v[66:67], 0, s[6:7]
	s_add_i32 m0, s5, 0x400
	s_nop 0
	s_mov_b64 s[6:7], 0x30780000
	global_load_lds_dwordx4 v[68:69], off
	s_add_i32 m0, s5, 0x8000
	v_lshl_add_u64 v[68:69], v[66:67], 0, s[6:7]
	s_mov_b64 s[6:7], 0x30784000
	global_load_lds_dwordx4 v[68:69], off
	v_lshl_add_u64 v[66:67], v[66:67], 0, s[6:7]
	s_add_i32 m0, s5, 0x8400
	s_nop 0
	global_load_lds_dwordx4 v[66:67], off

; __device__ __forceinline__ float h2f(unsigned short u) { return (float)__builtin_bit_cast(_Float16, u); }
; __device__ __forceinline__ void row_prefix4(float x, int tq, float& pre, float& tot) {
;     const auto s16 = __builtin_amdgcn_permlane16_swap(__float_as_uint(x), __float_as_uint(x), false, false);
;     const float ev = __uint_as_float(s16[0]), od = __uint_as_float(s16[1]), pr = ev + od;
;     const auto s32 = __builtin_amdgcn_permlane32_swap(__float_as_uint(pr), __float_as_uint(pr), false, false);
;     const float lo = __uint_as_float(s32[0]), hi = __uint_as_float(s32[1]);
;     tot = lo + hi; pre = tq == 0 ? 0.f : tq == 1 ? ev : tq == 2 ? lo : lo + ev;
; }
; template <bool FULL>
; __device__ __forceinline__ void hgrn_prep(char* lds, int s, int w, int kc, int tq, int kpos, float& gsum, s16x4& vfrag, u32x2& gvp) {
;     ...
;     float lf[4]; unsigned short qv[4], vv[4], gv[4];
; #pragma unroll
;     for (int j = 0; j < 4; ++j) { const int e = (4 * tq + j) * 128 + 16 * w + kc; lf[j] = h2f(*(const unsigned short*)(raw + e * 2)); vv[j] = *(const unsigned short*)(raw + 12288 + e * 2);
;         if (FULL) { qv[j] = *(const unsigned short*)(raw + 8192 + e * 2); gv[j] = *(const unsigned short*)(raw + 16384 + e * 2); } }
;     float G[4], glast;
;     { const float c0 = lf[0], c1 = c0 + lf[1], c2 = c1 + lf[2], c3 = c2 + lf[3];
;       float pre; row_prefix4(c3, tq, pre, glast);
;       G[0] = pre + c0; G[1] = pre + c1; G[2] = pre + c2; G[3] = pre + c3; }
.LBB0_2470:
	s_or_b64 exec, exec, s[38:39]
	v_lshlrev_b32_e32 v71, 1, v63
	s_waitcnt vmcnt(0)
	v_lshlrev_b32_e32 v4, 10, v66
	v_lshl_or_b32 v5, s4, 5, v71
	s_waitcnt lgkmcnt(0)
	s_barrier
	v_add3_u32 v7, v5, v4, 0
	ds_read_u16 v4, v7 offset:28672
	ds_read_u16 v5, v7 offset:28928
	ds_read_u16 v6, v7 offset:29184
	ds_read_u16 v17, v7 offset:29440
	v_cmp_lt_i32_e32 vcc, 0, v66
	s_waitcnt lgkmcnt(3)
	v_cvt_f32_f16_e32 v68, v4
	s_waitcnt lgkmcnt(2)
	v_cvt_f32_f16_e32 v62, v5
	s_waitcnt lgkmcnt(1)
	v_cvt_f32_f16_e32 v60, v6
	s_waitcnt lgkmcnt(0)
	v_cvt_f32_f16_e32 v37, v17
	ds_read_u16 v17, v7 offset:40960
	ds_read_u16 v69, v7 offset:36864
	ds_read_u16 v18, v7 offset:41216
	ds_read_u16 v67, v7 offset:37120
	ds_read_u16 v19, v7 offset:41472
	ds_read_u16 v61, v7 offset:37376
	ds_read_u16 v27, v7 offset:41728
	s_nop 0
	ds_read_u16 v39, v7 offset:37632
	ds_read_u16 v33, v7 offset:45056
	ds_read_u16 v35, v7 offset:45312
	ds_read_u16 v29, v7 offset:45568
	ds_read_u16 v31, v7 offset:45824
	v_add_f32_e32 v72, v68, v62
	v_add_f32_e32 v5, v72, v60
	v_add_f32_e32 v70, v5, v37
	v_mov_b32_e32 v73, v70
	v_mov_b32_e32 v4, v70
	s_nop 1
	v_permlane16_swap_b32_e32 v73, v4
	v_add_f32_e32 v4, v73, v4
	v_mov_b32_e32 v6, v4
	s_nop 1
	v_permlane32_swap_b32_e32 v4, v6
	v_mov_b32_e32 v7, 0
	s_and_saveexec_b64 s[38:39], vcc
	s_cbranch_execz .LBB0_2401
	v_cmp_ne_u32_e32 vcc, 1, v66
	s_and_saveexec_b64 s[14:15], vcc
	s_xor_b64 s[46:47], exec, s[14:15]
	v_add_f32_e32 v7, v73, v4
	v_cmp_eq_u32_e32 vcc, 2, v66
	s_nop 1
	v_cndmask_b32_e32 v7, v7, v4, vcc
	s_andn2_saveexec_b64 s[46:47], s[46:47]
	s_cbranch_execz .LBB0_2400
	v_mov_b32_e32 v7, v73
	s_branch .LBB0_2400
	s_nop 0
